# UQ epilogue: the four gain pieces of each row group loaded together (dead registers), counted waits
# speedup vs baseline: 1.0003x; 1.0003x over previous
.LBB0_1244:
	s_or_saveexec_b64 s[8:9], s[8:9]
	v_mov_b64_e32 v[134:135], 0x1a33d700
	s_xor_b64 exec, exec, s[8:9]
	v_mov_b64_e32 v[130:131], s[22:23]
	v_mad_i64_i32 v[130:131], s[34:35], v170, s56, v[130:131]
	v_ashrrev_i32_e32 v171, 31, v170
	s_mov_b64 s[34:35], 0x1243df00
	v_lshl_add_u64 v[130:131], v[130:131], 0, s[34:35]
	v_mov_b32_e32 v162, 0
	v_mov_b64_e32 v[134:135], 0x1c73d700
	s_andn2_b64 s[20:21], s[20:21], exec
	v_mov_b64_e32 v[132:133], v[170:171]
	s_or_b64 exec, exec, s[8:9]
	v_and_b32_e32 v137, 64, v215
	v_lshrrev_b32_e32 v0, 2, v136
	v_xor_b32_e32 v136, 16, v215
	v_add_u32_e32 v137, 64, v137
	v_cmp_lt_i32_e32 vcc, v136, v137
	v_and_b32_e32 v163, 12, v0
	v_lshlrev_b32_e32 v0, 2, v163
	v_cndmask_b32_e32 v136, v215, v136, vcc
	v_lshlrev_b32_e32 v171, 2, v136
	v_xor_b32_e32 v136, 32, v215
	v_cmp_lt_i32_e32 vcc, v136, v137
	s_mov_b64 s[8:9], 0x7b700
	v_lshl_add_u64 v[134:135], s[22:23], 0, v[134:135]
	v_cndmask_b32_e32 v136, v215, v136, vcc
	v_lshlrev_b32_e32 v196, 2, v136
	v_lshl_add_u64 v[136:137], s[22:23], 0, v[0:1]
	v_lshl_add_u64 v[166:167], v[136:137], 0, s[8:9]
	s_mov_b64 s[8:9], 0x7c700
	v_lshlrev_b64 v[132:133], 11, v[132:133]
	v_lshl_add_u64 v[138:139], v[130:131], 0, v[0:1]
	v_lshl_add_u64 v[168:169], v[136:137], 0, s[8:9]
	v_lshl_add_u64 v[164:165], v[134:135], 0, v[132:133]
	global_load_dwordx4 v[130:133], v[138:139], off
	global_load_dwordx4 v[134:137], v[138:139], off offset:64
	global_load_dwordx4 v[142:145], v[138:139], off offset:128
	s_nop 0
	global_load_dwordx4 v[138:141], v[138:139], off offset:192
	v_lshlrev_b32_e32 v172, 1, v163
	v_mov_b32_e32 v173, v1
	v_lshl_add_u64 v[164:165], v[164:165], 0, v[172:173]
	s_waitcnt vmcnt(4)
	v_and_b32_e32 v174, 0xfc0, v162
	v_mov_b32_e32 v175, v1
	v_lshl_add_u64 v[184:185], v[166:167], 0, v[174:175]
	v_lshl_add_u64 v[180:181], v[168:169], 0, v[174:175]
	v_lshlrev_b32_e32 v162, 6, v162
	v_pk_mul_f32 v[174:175], v[118:119], v[118:119]
	v_and_b32_e32 v162, 0x3c0, v162
	v_mov_b32_e32 v163, v1
	v_lshl_add_u64 v[182:183], v[166:167], 0, v[162:163]
	v_lshl_add_u64 v[176:177], v[168:169], 0, v[162:163]
	v_pk_mul_f32 v[162:163], v[120:121], v[120:121]
	s_lshl_b32 s38, s62, 2
	s_waitcnt vmcnt(2)
	v_mul_f32_e32 v146, v134, v134
	v_mul_f32_e32 v147, v135, v135
	v_fmac_f32_e32 v146, v130, v130
	v_fmac_f32_e32 v147, v131, v131
	s_waitcnt vmcnt(1)
	v_fmac_f32_e32 v146, v142, v142
	v_fmac_f32_e32 v147, v143, v143
	s_waitcnt vmcnt(0)
	v_fmac_f32_e32 v146, v138, v138
	v_fmac_f32_e32 v147, v139, v139
	v_add_f32_e32 v146, v146, v147
	v_mul_f32_e32 v147, v136, v136
	v_fmac_f32_e32 v147, v132, v132
	v_fmac_f32_e32 v147, v144, v144
	v_fmac_f32_e32 v147, v140, v140
	v_add_f32_e32 v146, v147, v146
	v_mul_f32_e32 v147, v137, v137
	v_fmac_f32_e32 v147, v133, v133
	v_fmac_f32_e32 v147, v145, v145
	v_fmac_f32_e32 v147, v141, v141
	v_add_f32_e32 v197, v147, v146
	v_fma_f32 v173, v126, v126, v197
	v_fmac_f32_e32 v173, v127, v127
	v_fmac_f32_e32 v173, v128, v128
	v_fmac_f32_e32 v173, v129, v129
	v_fmac_f32_e32 v173, v122, v122
	v_fmac_f32_e32 v173, v123, v123
	v_fmac_f32_e32 v173, v124, v124
	v_fmac_f32_e32 v173, v125, v125
	v_add_f32_e32 v173, v174, v173
	v_add_f32_e32 v173, v175, v173
	v_add_f32_e32 v162, v162, v173
	v_add_f32_e32 v173, v163, v162
	v_pk_mul_f32 v[174:175], v[114:115], v[114:115]
	v_pk_mul_f32 v[162:163], v[116:117], v[116:117]
	v_add_f32_e32 v173, v174, v173
	v_add_f32_e32 v173, v175, v173
	v_add_f32_e32 v162, v162, v173
	v_add_f32_e32 v162, v163, v162
	v_mov_b32_e32 v163, v162
	global_load_dwordx4 v[146:149], v0, s[72:73] offset:256
	global_load_dwordx4 v[150:153], v0, s[72:73] offset:320
	global_load_dwordx4 v[154:157], v0, s[72:73] offset:384
	global_load_dwordx4 v[158:161], v0, s[72:73] offset:448
	v_lshl_add_u64 v[174:175], v[164:165], 0, s[38:39]
	s_waitcnt lgkmcnt(0)
	s_nop 1
	v_permlane16_swap_b32_e32 v163, v162
	v_add_f32_e32 v162, v162, v163
	v_mov_b32_e32 v163, v162
	s_waitcnt lgkmcnt(0)
	s_nop 1
	v_permlane32_swap_b32_e32 v163, v162
	v_add_f32_e32 v162, v162, v163
	v_fmamk_f32 v162, v162, 0x3c000000, v178
	v_cmp_gt_f32_e32 vcc, s64, v162
	v_mul_f32_e32 v163, 0x4b800000, v162
	s_nop 0
	v_cndmask_b32_e32 v162, v162, v163, vcc
	v_rsq_f32_e32 v162, v162
	s_nop 0
	v_mul_f32_e32 v163, 0x45800000, v162
	v_cndmask_b32_e32 v186, v162, v163, vcc
	global_load_dwordx4 v[162:165], v0, s[72:73]
	global_load_dwordx4 v[188:191], v0, s[72:73] offset:64
	global_load_dwordx4 v[198:201], v0, s[72:73] offset:128
	global_load_dwordx4 v[202:205], v0, s[72:73] offset:192
	s_waitcnt vmcnt(3)
	v_pk_mul_f32 v[162:163], v[162:163], v[186:187] op_sel_hi:[1,0]
	s_nop 0
	v_pk_mul_f32 v[126:127], v[126:127], v[162:163]
	v_pk_mul_f32 v[162:163], v[164:165], v[186:187] op_sel_hi:[1,0]
	v_cvt_pk_bf16_f32 v126, v126, v127
	v_pk_mul_f32 v[128:129], v[128:129], v[162:163]
	s_nop 0
	v_cvt_pk_bf16_f32 v127, v128, v129
	global_store_dwordx2 v[174:175], v[126:127], off
	s_waitcnt vmcnt(3)
	v_pk_mul_f32 v[126:127], v[188:189], v[186:187] op_sel_hi:[1,0]
	s_nop 0
	v_pk_mul_f32 v[122:123], v[122:123], v[126:127]
	v_pk_mul_f32 v[126:127], v[190:191], v[186:187] op_sel_hi:[1,0]
	v_cvt_pk_bf16_f32 v122, v122, v123
	v_pk_mul_f32 v[124:125], v[124:125], v[126:127]
	v_mov_b32_e32 v128, v157
	v_cvt_pk_bf16_f32 v123, v124, v125
	global_store_dwordx2 v[174:175], v[122:123], off offset:32
	v_mov_b32_e32 v129, v161
	s_waitcnt vmcnt(3)
	v_pk_mul_f32 v[122:123], v[198:199], v[186:187] op_sel_hi:[1,0]
	s_nop 0
	v_pk_mul_f32 v[118:119], v[118:119], v[122:123]
	v_pk_mul_f32 v[122:123], v[200:201], v[186:187] op_sel_hi:[1,0]
	v_cvt_pk_bf16_f32 v118, v118, v119
	v_pk_mul_f32 v[120:121], v[120:121], v[122:123]
	s_nop 0
	v_cvt_pk_bf16_f32 v119, v120, v121
	global_store_dwordx2 v[174:175], v[118:119], off offset:64
	s_waitcnt vmcnt(3)
	v_pk_mul_f32 v[118:119], v[202:203], v[186:187] op_sel_hi:[1,0]
	s_nop 0
	v_pk_mul_f32 v[114:115], v[114:115], v[118:119]
	v_pk_mul_f32 v[118:119], v[204:205], v[186:187] op_sel_hi:[1,0]
	v_cvt_pk_bf16_f32 v114, v114, v115
	v_pk_mul_f32 v[116:117], v[116:117], v[118:119]
	v_mov_b32_e32 v120, v149
	v_cvt_pk_bf16_f32 v115, v116, v117
	global_store_dwordx2 v[174:175], v[114:115], off offset:96
	v_pk_mul_f32 v[114:115], v[130:131], v[186:187] op_sel_hi:[1,0]
	v_mov_b32_e32 v121, v153
	v_pk_mul_f32 v[124:125], v[146:147], v[114:115]
	v_pk_mul_f32 v[114:115], v[134:135], v[186:187] op_sel_hi:[1,0]
	s_nop 0
	v_pk_mul_f32 v[122:123], v[150:151], v[114:115]
	v_pk_mul_f32 v[114:115], v[142:143], v[186:187] op_sel_hi:[1,0]
	s_nop 0
	v_pk_mul_f32 v[118:119], v[154:155], v[114:115]
	v_pk_mul_f32 v[114:115], v[138:139], v[186:187] op_sel_hi:[1,0]
	s_nop 0
	v_pk_mul_f32 v[116:117], v[158:159], v[114:115]
	v_mul_f32_e32 v114, v132, v186
	v_mul_f32_e32 v164, v148, v114
	v_mul_f32_e32 v114, v136, v186
	v_mul_f32_e32 v188, v152, v114
	v_mul_f32_e32 v114, v144, v186
	v_mul_f32_e32 v190, v156, v114
	v_mul_f32_e32 v114, v140, v186
	v_mul_f32_e32 v192, v160, v114
	v_mov_b32_e32 v114, v133
	v_mov_b32_e32 v115, v137
	v_pk_mul_f32 v[126:127], v[114:115], v[186:187] op_sel_hi:[1,0]
	s_nop 0
	v_pk_mul_f32 v[194:195], v[120:121], v[126:127]
	v_mov_b32_e32 v126, v145
	v_mov_b32_e32 v127, v141
	v_pk_mul_f32 v[162:163], v[126:127], v[186:187] op_sel_hi:[1,0]
	s_nop 0
	v_pk_mul_f32 v[186:187], v[128:129], v[162:163]
	s_and_saveexec_b64 s[8:9], s[20:21]
	s_cbranch_execz .LBB0_1248
	global_load_dwordx4 v[198:201], v[184:185], off
	global_load_dwordx4 v[202:205], v[180:181], off
	global_load_dwordx4 v[206:209], v[182:183], off
	global_load_dwordx4 v[216:219], v[176:177], off
	s_waitcnt vmcnt(3)
	v_mul_f32_e32 v228, v164, v200
	s_waitcnt vmcnt(2)
	v_pk_mul_f32 v[162:163], v[122:123], v[202:203]
	v_mul_f32_e32 v230, v188, v204
	v_mul_f32_e32 v188, v188, v200
	v_mov_b32_e32 v200, v205
	v_pk_mul_f32 v[202:203], v[124:125], v[202:203]
	s_waitcnt vmcnt(0)
	v_mul_f32_e32 v236, v192, v218
	v_mul_f32_e32 v238, v190, v218
	v_pk_fma_f32 v[124:125], v[124:125], v[198:199], v[162:163] neg_lo:[0,0,1] neg_hi:[0,0,1]
	v_pk_mul_f32 v[162:163], v[194:195], v[200:201]
	v_mov_b32_e32 v218, v209
	v_mul_f32_e32 v232, v164, v204
	v_mul_f32_e32 v234, v190, v208
	v_mul_f32_e32 v192, v192, v208
	v_mov_b32_e32 v204, v201
	v_mov_b32_e32 v189, v163
	v_mov_b32_e32 v233, v162
	v_pk_mul_f32 v[162:163], v[186:187], v[218:219]
	v_mov_b32_e32 v208, v219
	v_pk_mul_f32 v[164:165], v[194:195], v[204:205]
	v_mov_b32_e32 v235, v162
	v_mov_b32_e32 v237, v163
	v_pk_mul_f32 v[162:163], v[186:187], v[208:209]
	v_mov_b32_e32 v229, v164
	v_mov_b32_e32 v231, v165
	v_mov_b32_e32 v193, v163
	v_mov_b32_e32 v239, v162
	v_pk_mul_f32 v[226:227], v[116:117], v[216:217]
	v_pk_mul_f32 v[216:217], v[118:119], v[216:217]
	v_pk_add_f32 v[164:165], v[228:229], v[230:231] neg_lo:[0,1] neg_hi:[0,1]
	v_pk_add_f32 v[188:189], v[188:189], v[232:233]
	v_pk_add_f32 v[190:191], v[234:235], v[236:237] neg_lo:[0,1] neg_hi:[0,1]
	v_pk_add_f32 v[192:193], v[192:193], v[238:239]
	v_pk_fma_f32 v[122:123], v[122:123], v[198:199], v[202:203]
	v_pk_fma_f32 v[118:119], v[118:119], v[206:207], v[226:227] neg_lo:[0,0,1] neg_hi:[0,0,1]
	v_pk_fma_f32 v[116:117], v[116:117], v[206:207], v[216:217]
	v_mov_b32_e32 v194, v165
	v_mov_b32_e32 v195, v189
	v_mov_b32_e32 v186, v191
	v_mov_b32_e32 v187, v193

.LBB0_1256:
	s_or_saveexec_b64 s[8:9], s[8:9]
	v_mov_b64_e32 v[102:103], s[68:69]
	s_xor_b64 exec, exec, s[8:9]
	v_mov_b64_e32 v[98:99], s[22:23]
	v_mad_i64_i32 v[98:99], s[34:35], v100, s56, v[98:99]
	s_mov_b64 s[34:35], 0x1243df00
	v_ashrrev_i32_e32 v101, 31, v100
	v_lshl_add_u64 v[98:99], v[98:99], 0, s[34:35]
	v_mov_b32_e32 v130, 0
	v_mov_b64_e32 v[102:103], s[80:81]
	s_andn2_b64 s[20:21], s[20:21], exec
	s_or_b64 exec, exec, s[8:9]
	v_lshlrev_b64 v[100:101], 11, v[100:101]
	v_lshl_add_u64 v[106:107], v[98:99], 0, v[0:1]
	v_lshl_add_u64 v[132:133], v[102:103], 0, v[100:101]
	global_load_dwordx4 v[98:101], v[106:107], off
	global_load_dwordx4 v[102:105], v[106:107], off offset:64
	global_load_dwordx4 v[110:113], v[106:107], off offset:128
	s_nop 0
	global_load_dwordx4 v[106:109], v[106:107], off offset:192
	v_and_b32_e32 v134, 0xfc0, v130
	v_mov_b32_e32 v135, v1
	v_lshl_add_u64 v[142:143], v[166:167], 0, v[134:135]
	v_lshl_add_u64 v[138:139], v[168:169], 0, v[134:135]
	v_lshlrev_b32_e32 v130, 6, v130
	v_pk_mul_f32 v[134:135], v[86:87], v[86:87]
	v_and_b32_e32 v130, 0x7c0, v130
	v_mov_b32_e32 v131, v1
	v_lshl_add_u64 v[140:141], v[166:167], 0, v[130:131]
	v_lshl_add_u64 v[136:137], v[168:169], 0, v[130:131]
	v_pk_mul_f32 v[130:131], v[88:89], v[88:89]
	s_lshl_b32 s8, s62, 1
	v_mov_b32_e32 v173, v1
	v_lshl_add_u64 v[132:133], v[132:133], 0, v[172:173]
	s_lshl_b32 s38, s8, 1
	s_waitcnt vmcnt(2)
	v_mul_f32_e32 v114, v102, v102
	v_mul_f32_e32 v115, v103, v103
	v_fmac_f32_e32 v114, v98, v98
	v_fmac_f32_e32 v115, v99, v99
	s_waitcnt vmcnt(1)
	v_fmac_f32_e32 v114, v110, v110
	v_fmac_f32_e32 v115, v111, v111
	s_waitcnt vmcnt(0)
	v_fmac_f32_e32 v114, v106, v106
	v_fmac_f32_e32 v115, v107, v107
	v_add_f32_e32 v114, v114, v115
	v_mul_f32_e32 v115, v104, v104
	v_fmac_f32_e32 v115, v100, v100
	v_fmac_f32_e32 v115, v112, v112
	v_fmac_f32_e32 v115, v108, v108
	v_add_f32_e32 v114, v115, v114
	v_mul_f32_e32 v115, v105, v105
	v_fmac_f32_e32 v115, v101, v101
	v_fmac_f32_e32 v115, v113, v113
	v_fmac_f32_e32 v115, v109, v109
	v_add_f32_e32 v152, v115, v114
	v_fma_f32 v144, v94, v94, v152
	v_fmac_f32_e32 v144, v95, v95
	v_fmac_f32_e32 v144, v96, v96
	v_fmac_f32_e32 v144, v97, v97
	v_fmac_f32_e32 v144, v90, v90
	v_fmac_f32_e32 v144, v91, v91
	v_fmac_f32_e32 v144, v92, v92
	v_fmac_f32_e32 v144, v93, v93
	v_add_f32_e32 v134, v134, v144
	v_add_f32_e32 v134, v135, v134
	v_add_f32_e32 v130, v130, v134
	v_add_f32_e32 v144, v131, v130
	v_pk_mul_f32 v[134:135], v[82:83], v[82:83]
	v_pk_mul_f32 v[130:131], v[84:85], v[84:85]
	v_add_f32_e32 v134, v134, v144
	v_add_f32_e32 v134, v135, v134
	v_add_f32_e32 v130, v130, v134
	v_add_f32_e32 v130, v131, v130
	v_mov_b32_e32 v131, v130
	global_load_dwordx4 v[114:117], v[162:163], off offset:256
	global_load_dwordx4 v[118:121], v[162:163], off offset:320
	global_load_dwordx4 v[122:125], v[162:163], off offset:384
	global_load_dwordx4 v[126:129], v[162:163], off offset:448
	v_lshl_add_u64 v[134:135], v[132:133], 0, s[38:39]
	s_waitcnt lgkmcnt(0)
	s_nop 1
	v_permlane16_swap_b32_e32 v131, v130
	v_add_f32_e32 v130, v130, v131
	v_mov_b32_e32 v131, v130
	s_waitcnt lgkmcnt(0)
	s_nop 1
	v_permlane32_swap_b32_e32 v131, v130
	v_add_f32_e32 v130, v130, v131
	v_fmamk_f32 v130, v130, 0x3c000000, v178
	v_cmp_gt_f32_e32 vcc, s64, v130
	v_mul_f32_e32 v131, 0x4b800000, v130
	s_nop 0
	v_cndmask_b32_e32 v130, v130, v131, vcc
	v_rsq_f32_e32 v130, v130
	s_nop 0
	v_mul_f32_e32 v131, 0x45800000, v130
	v_cndmask_b32_e32 v144, v130, v131, vcc
	global_load_dwordx4 v[130:133], v[162:163], off
	global_load_dwordx4 v[146:149], v[162:163], off offset:64
	global_load_dwordx4 v[154:157], v[162:163], off offset:128
	global_load_dwordx4 v[174:177], v[162:163], off offset:192
	s_waitcnt vmcnt(3)
	v_pk_mul_f32 v[130:131], v[130:131], v[144:145] op_sel_hi:[1,0]
	s_nop 0
	v_pk_mul_f32 v[94:95], v[94:95], v[130:131]
	v_pk_mul_f32 v[130:131], v[132:133], v[144:145] op_sel_hi:[1,0]
	v_cvt_pk_bf16_f32 v94, v94, v95
	v_pk_mul_f32 v[96:97], v[96:97], v[130:131]
	s_nop 0
	v_cvt_pk_bf16_f32 v95, v96, v97
	global_store_dwordx2 v[134:135], v[94:95], off
	s_waitcnt vmcnt(3)
	v_pk_mul_f32 v[94:95], v[146:147], v[144:145] op_sel_hi:[1,0]
	s_nop 0
	v_pk_mul_f32 v[90:91], v[90:91], v[94:95]
	v_pk_mul_f32 v[94:95], v[148:149], v[144:145] op_sel_hi:[1,0]
	v_cvt_pk_bf16_f32 v90, v90, v91
	v_pk_mul_f32 v[92:93], v[92:93], v[94:95]
	v_mov_b32_e32 v96, v125
	v_cvt_pk_bf16_f32 v91, v92, v93
	global_store_dwordx2 v[134:135], v[90:91], off offset:32
	v_mov_b32_e32 v97, v129
	s_waitcnt vmcnt(3)
	v_pk_mul_f32 v[90:91], v[154:155], v[144:145] op_sel_hi:[1,0]
	s_nop 0
	v_pk_mul_f32 v[86:87], v[86:87], v[90:91]
	v_pk_mul_f32 v[90:91], v[156:157], v[144:145] op_sel_hi:[1,0]
	v_cvt_pk_bf16_f32 v86, v86, v87
	v_pk_mul_f32 v[88:89], v[88:89], v[90:91]
	s_nop 0
	v_cvt_pk_bf16_f32 v87, v88, v89
	global_store_dwordx2 v[134:135], v[86:87], off offset:64
	s_waitcnt vmcnt(3)
	v_pk_mul_f32 v[86:87], v[174:175], v[144:145] op_sel_hi:[1,0]
	s_nop 0
	v_pk_mul_f32 v[82:83], v[82:83], v[86:87]
	v_pk_mul_f32 v[86:87], v[176:177], v[144:145] op_sel_hi:[1,0]
	v_cvt_pk_bf16_f32 v82, v82, v83
	v_pk_mul_f32 v[84:85], v[84:85], v[86:87]
	s_nop 0
	v_cvt_pk_bf16_f32 v83, v84, v85
	global_store_dwordx2 v[134:135], v[82:83], off offset:96
	v_pk_mul_f32 v[82:83], v[98:99], v[144:145] op_sel_hi:[1,0]
	v_mov_b32_e32 v84, v117
	v_pk_mul_f32 v[94:95], v[114:115], v[82:83]
	v_pk_mul_f32 v[82:83], v[102:103], v[144:145] op_sel_hi:[1,0]
	v_mov_b32_e32 v85, v121
	v_pk_mul_f32 v[92:93], v[118:119], v[82:83]
	v_pk_mul_f32 v[82:83], v[110:111], v[144:145] op_sel_hi:[1,0]
	s_nop 0
	v_pk_mul_f32 v[88:89], v[122:123], v[82:83]
	v_pk_mul_f32 v[82:83], v[106:107], v[144:145] op_sel_hi:[1,0]
	s_nop 0
	v_pk_mul_f32 v[86:87], v[126:127], v[82:83]
	v_mul_f32_e32 v82, v100, v144
	v_mul_f32_e32 v130, v116, v82
	v_mul_f32_e32 v82, v104, v144
	v_mul_f32_e32 v132, v120, v82
	v_mul_f32_e32 v82, v112, v144
	v_mul_f32_e32 v146, v124, v82
	v_mul_f32_e32 v82, v108, v144
	v_mul_f32_e32 v148, v128, v82
	v_mov_b32_e32 v82, v101
	v_mov_b32_e32 v83, v105
	v_pk_mul_f32 v[90:91], v[82:83], v[144:145] op_sel_hi:[1,0]
	s_nop 0
	v_pk_mul_f32 v[150:151], v[84:85], v[90:91]
	v_mov_b32_e32 v90, v113
	v_mov_b32_e32 v91, v109
	v_pk_mul_f32 v[144:145], v[90:91], v[144:145] op_sel_hi:[1,0]
	s_nop 0
	v_pk_mul_f32 v[144:145], v[96:97], v[144:145]
	s_and_saveexec_b64 s[8:9], s[20:21]
	s_cbranch_execz .LBB0_1260
	global_load_dwordx4 v[154:157], v[142:143], off
	global_load_dwordx4 v[158:161], v[138:139], off
	global_load_dwordx4 v[174:177], v[140:141], off
	global_load_dwordx4 v[180:183], v[136:137], off
	s_waitcnt vmcnt(3)
	v_mul_f32_e32 v186, v130, v156
	s_waitcnt vmcnt(2)
	v_mul_f32_e32 v188, v132, v160
	v_mul_f32_e32 v132, v132, v156
	v_mov_b32_e32 v156, v161
	v_mul_f32_e32 v190, v130, v160
	s_waitcnt vmcnt(1)
	v_mul_f32_e32 v192, v146, v176
	s_waitcnt vmcnt(0)
	v_mul_f32_e32 v194, v148, v182
	v_mul_f32_e32 v148, v148, v176
	v_mul_f32_e32 v198, v146, v182
	v_mov_b32_e32 v160, v157
	v_pk_mul_f32 v[146:147], v[150:151], v[156:157]
	v_mov_b32_e32 v182, v177
	v_mov_b32_e32 v176, v183
	v_pk_mul_f32 v[130:131], v[150:151], v[160:161]
	v_mov_b32_e32 v133, v147
	v_mov_b32_e32 v191, v146
	v_pk_mul_f32 v[146:147], v[144:145], v[182:183]
	v_pk_mul_f32 v[144:145], v[144:145], v[176:177]
	v_mov_b32_e32 v187, v130
	v_mov_b32_e32 v189, v131
	v_mov_b32_e32 v193, v146
	v_mov_b32_e32 v195, v147
	v_mov_b32_e32 v149, v145
	v_mov_b32_e32 v199, v144
	v_pk_mul_f32 v[164:165], v[92:93], v[158:159]
	v_pk_mul_f32 v[158:159], v[94:95], v[158:159]
	v_pk_mul_f32 v[184:185], v[86:87], v[180:181]
	v_pk_mul_f32 v[180:181], v[88:89], v[180:181]
	v_pk_add_f32 v[130:131], v[186:187], v[188:189] neg_lo:[0,1] neg_hi:[0,1]
	v_pk_add_f32 v[132:133], v[132:133], v[190:191]
	v_pk_add_f32 v[146:147], v[192:193], v[194:195] neg_lo:[0,1] neg_hi:[0,1]
	v_pk_add_f32 v[148:149], v[148:149], v[198:199]
	v_pk_fma_f32 v[94:95], v[94:95], v[154:155], v[164:165] neg_lo:[0,0,1] neg_hi:[0,0,1]
	v_pk_fma_f32 v[92:93], v[92:93], v[154:155], v[158:159]
	v_pk_fma_f32 v[88:89], v[88:89], v[174:175], v[184:185] neg_lo:[0,0,1] neg_hi:[0,0,1]
	v_pk_fma_f32 v[86:87], v[86:87], v[174:175], v[180:181]
	v_mov_b32_e32 v150, v131
	v_mov_b32_e32 v151, v133
	v_mov_b32_e32 v144, v147
	v_mov_b32_e32 v145, v149

.LBB0_1268:
	s_or_saveexec_b64 s[8:9], s[8:9]
	v_mov_b64_e32 v[70:71], s[68:69]
	s_xor_b64 exec, exec, s[8:9]
	v_mov_b64_e32 v[66:67], s[22:23]
	v_mad_i64_i32 v[66:67], s[34:35], v68, s56, v[66:67]
	s_mov_b64 s[34:35], 0x1243df00
	v_ashrrev_i32_e32 v69, 31, v68
	v_lshl_add_u64 v[66:67], v[66:67], 0, s[34:35]
	v_mov_b32_e32 v98, 0
	v_mov_b64_e32 v[70:71], s[80:81]
	s_andn2_b64 s[20:21], s[20:21], exec
	s_or_b64 exec, exec, s[8:9]
	v_lshlrev_b64 v[68:69], 11, v[68:69]
	v_lshl_add_u64 v[74:75], v[66:67], 0, v[0:1]
	v_lshl_add_u64 v[100:101], v[70:71], 0, v[68:69]
	global_load_dwordx4 v[66:69], v[74:75], off
	global_load_dwordx4 v[70:73], v[74:75], off offset:64
	global_load_dwordx4 v[78:81], v[74:75], off offset:128
	s_nop 0
	global_load_dwordx4 v[74:77], v[74:75], off offset:192
	v_and_b32_e32 v102, 0xfc0, v98
	v_mov_b32_e32 v103, v1
	v_lshl_add_u64 v[110:111], v[166:167], 0, v[102:103]
	v_lshl_add_u64 v[106:107], v[168:169], 0, v[102:103]
	v_lshlrev_b32_e32 v98, 6, v98
	v_pk_mul_f32 v[102:103], v[54:55], v[54:55]
	v_and_b32_e32 v98, 0xbc0, v98
	v_mov_b32_e32 v99, v1
	v_lshl_add_u64 v[108:109], v[166:167], 0, v[98:99]
	v_lshl_add_u64 v[104:105], v[168:169], 0, v[98:99]
	v_pk_mul_f32 v[98:99], v[56:57], v[56:57]
	v_mov_b32_e32 v173, v1
	v_lshl_add_u64 v[100:101], v[100:101], 0, v[172:173]
	s_waitcnt vmcnt(2)
	v_mul_f32_e32 v82, v70, v70
	v_mul_f32_e32 v83, v71, v71
	v_fmac_f32_e32 v82, v66, v66
	v_fmac_f32_e32 v83, v67, v67
	s_waitcnt vmcnt(1)
	v_fmac_f32_e32 v82, v78, v78
	v_fmac_f32_e32 v83, v79, v79
	s_waitcnt vmcnt(0)
	v_fmac_f32_e32 v82, v74, v74
	v_fmac_f32_e32 v83, v75, v75
	v_add_f32_e32 v82, v82, v83
	v_mul_f32_e32 v83, v72, v72
	v_fmac_f32_e32 v83, v68, v68
	v_fmac_f32_e32 v83, v80, v80
	v_fmac_f32_e32 v83, v76, v76
	v_add_f32_e32 v82, v83, v82
	v_mul_f32_e32 v83, v73, v73
	v_fmac_f32_e32 v83, v69, v69
	v_fmac_f32_e32 v83, v81, v81
	v_fmac_f32_e32 v83, v77, v77
	v_add_f32_e32 v120, v83, v82
	v_fma_f32 v112, v62, v62, v120
	v_fmac_f32_e32 v112, v63, v63
	v_fmac_f32_e32 v112, v64, v64
	v_fmac_f32_e32 v112, v65, v65
	v_fmac_f32_e32 v112, v58, v58
	v_fmac_f32_e32 v112, v59, v59
	v_fmac_f32_e32 v112, v60, v60
	v_fmac_f32_e32 v112, v61, v61
	v_add_f32_e32 v102, v102, v112
	v_add_f32_e32 v102, v103, v102
	v_add_f32_e32 v98, v98, v102
	v_add_f32_e32 v112, v99, v98
	v_pk_mul_f32 v[102:103], v[50:51], v[50:51]
	v_pk_mul_f32 v[98:99], v[52:53], v[52:53]
	v_add_f32_e32 v102, v102, v112
	v_add_f32_e32 v102, v103, v102
	v_add_f32_e32 v98, v98, v102
	v_add_f32_e32 v98, v99, v98
	v_mov_b32_e32 v99, v98
	global_load_dwordx4 v[82:85], v[162:163], off offset:256
	global_load_dwordx4 v[86:89], v[162:163], off offset:320
	global_load_dwordx4 v[90:93], v[162:163], off offset:384
	global_load_dwordx4 v[94:97], v[162:163], off offset:448
	v_lshl_add_u64 v[102:103], v[100:101], 0, s[38:39]
	s_waitcnt lgkmcnt(0)
	s_nop 1
	v_permlane16_swap_b32_e32 v99, v98
	v_add_f32_e32 v98, v98, v99
	v_mov_b32_e32 v99, v98
	s_waitcnt lgkmcnt(0)
	s_nop 1
	v_permlane32_swap_b32_e32 v99, v98
	v_add_f32_e32 v98, v98, v99
	v_fmamk_f32 v98, v98, 0x3c000000, v178
	v_cmp_gt_f32_e32 vcc, s64, v98
	v_mul_f32_e32 v99, 0x4b800000, v98
	s_nop 0
	v_cndmask_b32_e32 v98, v98, v99, vcc
	v_rsq_f32_e32 v98, v98
	s_nop 0
	v_mul_f32_e32 v99, 0x45800000, v98
	v_cndmask_b32_e32 v112, v98, v99, vcc
	global_load_dwordx4 v[98:101], v[162:163], off
	global_load_dwordx4 v[138:141], v[162:163], off offset:64
	global_load_dwordx4 v[142:145], v[162:163], off offset:128
	global_load_dwordx4 v[146:149], v[162:163], off offset:192
	s_waitcnt vmcnt(3)
	v_pk_mul_f32 v[98:99], v[98:99], v[112:113] op_sel_hi:[1,0]
	s_nop 0
	v_pk_mul_f32 v[62:63], v[62:63], v[98:99]
	v_pk_mul_f32 v[98:99], v[100:101], v[112:113] op_sel_hi:[1,0]
	v_cvt_pk_bf16_f32 v62, v62, v63
	v_pk_mul_f32 v[64:65], v[64:65], v[98:99]
	s_nop 0
	v_cvt_pk_bf16_f32 v63, v64, v65
	global_store_dwordx2 v[102:103], v[62:63], off
	s_waitcnt vmcnt(3)
	v_pk_mul_f32 v[62:63], v[138:139], v[112:113] op_sel_hi:[1,0]
	s_nop 0
	v_pk_mul_f32 v[58:59], v[58:59], v[62:63]
	v_pk_mul_f32 v[62:63], v[140:141], v[112:113] op_sel_hi:[1,0]
	v_cvt_pk_bf16_f32 v58, v58, v59
	v_pk_mul_f32 v[60:61], v[60:61], v[62:63]
	v_mov_b32_e32 v64, v93
	v_cvt_pk_bf16_f32 v59, v60, v61
	global_store_dwordx2 v[102:103], v[58:59], off offset:32
	v_mov_b32_e32 v65, v97
	s_waitcnt vmcnt(3)
	v_pk_mul_f32 v[58:59], v[142:143], v[112:113] op_sel_hi:[1,0]
	s_nop 0
	v_pk_mul_f32 v[54:55], v[54:55], v[58:59]
	v_pk_mul_f32 v[58:59], v[144:145], v[112:113] op_sel_hi:[1,0]
	v_cvt_pk_bf16_f32 v54, v54, v55
	v_pk_mul_f32 v[56:57], v[56:57], v[58:59]
	s_nop 0
	v_cvt_pk_bf16_f32 v55, v56, v57
	global_store_dwordx2 v[102:103], v[54:55], off offset:64
	s_waitcnt vmcnt(3)
	v_pk_mul_f32 v[54:55], v[146:147], v[112:113] op_sel_hi:[1,0]
	s_nop 0
	v_pk_mul_f32 v[50:51], v[50:51], v[54:55]
	v_pk_mul_f32 v[54:55], v[148:149], v[112:113] op_sel_hi:[1,0]
	v_cvt_pk_bf16_f32 v50, v50, v51
	v_pk_mul_f32 v[52:53], v[52:53], v[54:55]
	s_nop 0
	v_cvt_pk_bf16_f32 v51, v52, v53
	global_store_dwordx2 v[102:103], v[50:51], off offset:96
	v_pk_mul_f32 v[50:51], v[66:67], v[112:113] op_sel_hi:[1,0]
	v_mov_b32_e32 v52, v85
	v_pk_mul_f32 v[62:63], v[82:83], v[50:51]
	v_pk_mul_f32 v[50:51], v[70:71], v[112:113] op_sel_hi:[1,0]
	v_mov_b32_e32 v53, v89
	v_pk_mul_f32 v[60:61], v[86:87], v[50:51]
	v_pk_mul_f32 v[50:51], v[78:79], v[112:113] op_sel_hi:[1,0]
	s_nop 0
	v_pk_mul_f32 v[56:57], v[90:91], v[50:51]
	v_pk_mul_f32 v[50:51], v[74:75], v[112:113] op_sel_hi:[1,0]
	s_nop 0
	v_pk_mul_f32 v[54:55], v[94:95], v[50:51]
	v_mul_f32_e32 v50, v68, v112
	v_mul_f32_e32 v98, v84, v50
	v_mul_f32_e32 v50, v72, v112
	v_mul_f32_e32 v100, v88, v50
	v_mul_f32_e32 v50, v80, v112
	v_mul_f32_e32 v114, v92, v50
	v_mul_f32_e32 v50, v76, v112
	v_mul_f32_e32 v116, v96, v50
	v_mov_b32_e32 v50, v69
	v_mov_b32_e32 v51, v73
	v_pk_mul_f32 v[58:59], v[50:51], v[112:113] op_sel_hi:[1,0]
	s_nop 0
	v_pk_mul_f32 v[118:119], v[52:53], v[58:59]
	v_mov_b32_e32 v58, v81
	v_mov_b32_e32 v59, v77
	v_pk_mul_f32 v[112:113], v[58:59], v[112:113] op_sel_hi:[1,0]
	s_nop 0
	v_pk_mul_f32 v[112:113], v[64:65], v[112:113]
	s_and_saveexec_b64 s[8:9], s[20:21]
	s_cbranch_execz .LBB0_1272
	global_load_dwordx4 v[122:125], v[110:111], off
	global_load_dwordx4 v[126:129], v[106:107], off
	global_load_dwordx4 v[130:133], v[108:109], off
	global_load_dwordx4 v[134:137], v[104:105], off
	s_waitcnt vmcnt(3)
	v_mul_f32_e32 v142, v98, v124
	s_waitcnt vmcnt(2)
	v_mul_f32_e32 v144, v100, v128
	v_mul_f32_e32 v100, v100, v124
	v_mov_b32_e32 v124, v129
	v_mul_f32_e32 v146, v98, v128
	s_waitcnt vmcnt(1)
	v_mul_f32_e32 v148, v114, v132
	s_waitcnt vmcnt(0)
	v_mul_f32_e32 v150, v116, v136
	v_mul_f32_e32 v116, v116, v132
	v_mul_f32_e32 v152, v114, v136
	v_mov_b32_e32 v128, v125
	v_pk_mul_f32 v[114:115], v[118:119], v[124:125]
	v_mov_b32_e32 v136, v133
	v_mov_b32_e32 v132, v137
	v_pk_mul_f32 v[98:99], v[118:119], v[128:129]
	v_mov_b32_e32 v101, v115
	v_mov_b32_e32 v147, v114
	v_pk_mul_f32 v[114:115], v[112:113], v[136:137]
	v_pk_mul_f32 v[112:113], v[112:113], v[132:133]
	v_mov_b32_e32 v143, v98
	v_mov_b32_e32 v145, v99
	v_mov_b32_e32 v149, v114
	v_mov_b32_e32 v151, v115
	v_mov_b32_e32 v117, v113
	v_mov_b32_e32 v153, v112
	v_pk_mul_f32 v[138:139], v[60:61], v[126:127]
	v_pk_mul_f32 v[126:127], v[62:63], v[126:127]
	v_pk_mul_f32 v[140:141], v[54:55], v[134:135]
	v_pk_mul_f32 v[134:135], v[56:57], v[134:135]
	v_pk_add_f32 v[98:99], v[142:143], v[144:145] neg_lo:[0,1] neg_hi:[0,1]
	v_pk_add_f32 v[100:101], v[100:101], v[146:147]
	v_pk_add_f32 v[114:115], v[148:149], v[150:151] neg_lo:[0,1] neg_hi:[0,1]
	v_pk_add_f32 v[116:117], v[116:117], v[152:153]
	v_pk_fma_f32 v[62:63], v[62:63], v[122:123], v[138:139] neg_lo:[0,0,1] neg_hi:[0,0,1]
	v_pk_fma_f32 v[60:61], v[60:61], v[122:123], v[126:127]
	v_pk_fma_f32 v[56:57], v[56:57], v[130:131], v[140:141] neg_lo:[0,0,1] neg_hi:[0,0,1]
	v_pk_fma_f32 v[54:55], v[54:55], v[130:131], v[134:135]
	v_mov_b32_e32 v118, v99
	v_mov_b32_e32 v119, v101
	v_mov_b32_e32 v112, v115
	v_mov_b32_e32 v113, v117

.LBB0_1280:
	s_or_saveexec_b64 s[8:9], s[8:9]
	v_mov_b64_e32 v[38:39], s[68:69]
	s_xor_b64 exec, exec, s[8:9]
	v_mov_b64_e32 v[34:35], s[22:23]
	v_mad_i64_i32 v[34:35], s[22:23], v36, s56, v[34:35]
	s_mov_b64 s[22:23], 0x1243df00
	v_ashrrev_i32_e32 v37, 31, v36
	v_lshl_add_u64 v[34:35], v[34:35], 0, s[22:23]
	v_mov_b32_e32 v66, 0
	v_mov_b64_e32 v[38:39], s[80:81]
	s_andn2_b64 s[20:21], s[20:21], exec
	s_or_b64 exec, exec, s[8:9]
	v_lshlrev_b64 v[36:37], 11, v[36:37]
	v_lshl_add_u64 v[42:43], v[34:35], 0, v[0:1]
	v_lshl_add_u64 v[68:69], v[38:39], 0, v[36:37]
	global_load_dwordx4 v[34:37], v[42:43], off
	global_load_dwordx4 v[38:41], v[42:43], off offset:64
	global_load_dwordx4 v[46:49], v[42:43], off offset:128
	s_nop 0
	global_load_dwordx4 v[42:45], v[42:43], off offset:192
	v_pk_mul_f32 v[70:71], v[22:23], v[22:23]
	v_mov_b32_e32 v173, v1
	v_lshl_add_u64 v[68:69], v[68:69], 0, v[172:173]
	s_waitcnt vmcnt(2)
	v_mul_f32_e32 v0, v38, v38
	v_mul_f32_e32 v50, v39, v39
	v_fmac_f32_e32 v0, v34, v34
	v_fmac_f32_e32 v50, v35, v35
	s_waitcnt vmcnt(1)
	v_fmac_f32_e32 v0, v46, v46
	v_fmac_f32_e32 v50, v47, v47
	s_waitcnt vmcnt(0)
	v_fmac_f32_e32 v0, v42, v42
	v_fmac_f32_e32 v50, v43, v43
	v_add_f32_e32 v0, v0, v50
	v_mul_f32_e32 v50, v40, v40
	v_fmac_f32_e32 v50, v36, v36
	v_fmac_f32_e32 v50, v48, v48
	v_fmac_f32_e32 v50, v44, v44
	v_add_f32_e32 v0, v50, v0
	v_mul_f32_e32 v50, v41, v41
	v_fmac_f32_e32 v50, v37, v37
	v_fmac_f32_e32 v50, v49, v49
	v_fmac_f32_e32 v50, v45, v45
	v_add_f32_e32 v88, v50, v0
	v_and_b32_e32 v0, 0xfc0, v66
	v_lshl_add_u64 v[78:79], v[166:167], 0, v[0:1]
	v_lshl_add_u64 v[74:75], v[168:169], 0, v[0:1]
	v_lshlrev_b32_e32 v0, 6, v66
	v_and_b32_e32 v0, 0xfc0, v0
	v_lshl_add_u64 v[76:77], v[166:167], 0, v[0:1]
	v_lshl_add_u64 v[72:73], v[168:169], 0, v[0:1]
	v_fma_f32 v0, v30, v30, v88
	v_fmac_f32_e32 v0, v31, v31
	v_fmac_f32_e32 v0, v32, v32
	v_fmac_f32_e32 v0, v33, v33
	v_fmac_f32_e32 v0, v26, v26
	v_fmac_f32_e32 v0, v27, v27
	v_fmac_f32_e32 v0, v28, v28
	v_fmac_f32_e32 v0, v29, v29
	v_add_f32_e32 v0, v70, v0
	v_pk_mul_f32 v[66:67], v[24:25], v[24:25]
	v_add_f32_e32 v0, v71, v0
	v_add_f32_e32 v0, v66, v0
	v_add_f32_e32 v0, v67, v0
	v_pk_mul_f32 v[70:71], v[18:19], v[18:19]
	v_pk_mul_f32 v[66:67], v[20:21], v[20:21]
	v_add_f32_e32 v0, v70, v0
	v_add_f32_e32 v0, v71, v0
	v_add_f32_e32 v0, v66, v0
	v_add_f32_e32 v0, v67, v0
	v_mov_b32_e32 v66, v0
	global_load_dwordx4 v[50:53], v[162:163], off offset:256
	global_load_dwordx4 v[54:57], v[162:163], off offset:320
	global_load_dwordx4 v[58:61], v[162:163], off offset:384
	global_load_dwordx4 v[62:65], v[162:163], off offset:448
	v_lshl_add_u64 v[70:71], v[68:69], 0, s[38:39]
	s_waitcnt lgkmcnt(0)
	s_nop 1
	v_permlane16_swap_b32_e32 v66, v0
	v_add_f32_e32 v0, v0, v66
	v_mov_b32_e32 v66, v0
	s_waitcnt lgkmcnt(0)
	s_nop 1
	v_permlane32_swap_b32_e32 v66, v0
	v_add_f32_e32 v0, v0, v66
	v_fmamk_f32 v0, v0, 0x3c000000, v178
	v_cmp_gt_f32_e32 vcc, s64, v0
	v_mul_f32_e32 v66, 0x4b800000, v0
	s_nop 0
	v_cndmask_b32_e32 v0, v0, v66, vcc
	v_rsq_f32_e32 v0, v0
	s_nop 0
	v_mul_f32_e32 v66, 0x45800000, v0
	v_cndmask_b32_e32 v0, v0, v66, vcc
	global_load_dwordx4 v[66:69], v[162:163], off
	global_load_dwordx4 v[80:83], v[162:163], off offset:64
	global_load_dwordx4 v[84:87], v[162:163], off offset:128
	global_load_dwordx4 v[90:93], v[162:163], off offset:192
	s_waitcnt vmcnt(3)
	v_pk_mul_f32 v[66:67], v[66:67], v[0:1] op_sel_hi:[1,0]
	s_nop 0
	v_pk_mul_f32 v[30:31], v[30:31], v[66:67]
	v_pk_mul_f32 v[66:67], v[68:69], v[0:1] op_sel_hi:[1,0]
	v_cvt_pk_bf16_f32 v30, v30, v31
	v_pk_mul_f32 v[32:33], v[32:33], v[66:67]
	s_nop 0
	v_cvt_pk_bf16_f32 v31, v32, v33
	global_store_dwordx2 v[70:71], v[30:31], off
	s_waitcnt vmcnt(3)
	v_pk_mul_f32 v[30:31], v[80:81], v[0:1] op_sel_hi:[1,0]
	s_nop 0
	v_pk_mul_f32 v[26:27], v[26:27], v[30:31]
	v_pk_mul_f32 v[30:31], v[82:83], v[0:1] op_sel_hi:[1,0]
	v_cvt_pk_bf16_f32 v26, v26, v27
	v_pk_mul_f32 v[28:29], v[28:29], v[30:31]
	s_nop 0
	v_cvt_pk_bf16_f32 v27, v28, v29
	global_store_dwordx2 v[70:71], v[26:27], off offset:32
	s_waitcnt vmcnt(3)
	v_pk_mul_f32 v[26:27], v[84:85], v[0:1] op_sel_hi:[1,0]
	s_nop 0
	v_pk_mul_f32 v[22:23], v[22:23], v[26:27]
	v_pk_mul_f32 v[26:27], v[86:87], v[0:1] op_sel_hi:[1,0]
	v_cvt_pk_bf16_f32 v22, v22, v23
	v_pk_mul_f32 v[24:25], v[24:25], v[26:27]
	v_mov_b32_e32 v26, v61
	v_cvt_pk_bf16_f32 v23, v24, v25
	global_store_dwordx2 v[70:71], v[22:23], off offset:64
	v_mov_b32_e32 v27, v65
	s_waitcnt vmcnt(3)
	v_pk_mul_f32 v[22:23], v[90:91], v[0:1] op_sel_hi:[1,0]
	s_nop 0
	v_pk_mul_f32 v[18:19], v[18:19], v[22:23]
	v_pk_mul_f32 v[22:23], v[92:93], v[0:1] op_sel_hi:[1,0]
	v_cvt_pk_bf16_f32 v18, v18, v19
	v_pk_mul_f32 v[20:21], v[20:21], v[22:23]
	s_nop 0
	v_cvt_pk_bf16_f32 v19, v20, v21
	global_store_dwordx2 v[70:71], v[18:19], off offset:96
	v_pk_mul_f32 v[18:19], v[34:35], v[0:1] op_sel_hi:[1,0]
	v_mov_b32_e32 v20, v53
	v_pk_mul_f32 v[32:33], v[50:51], v[18:19]
	v_pk_mul_f32 v[18:19], v[38:39], v[0:1] op_sel_hi:[1,0]
	v_mov_b32_e32 v21, v57
	v_pk_mul_f32 v[30:31], v[54:55], v[18:19]
	v_pk_mul_f32 v[18:19], v[46:47], v[0:1] op_sel_hi:[1,0]
	s_nop 0
	v_pk_mul_f32 v[28:29], v[58:59], v[18:19]
	v_pk_mul_f32 v[18:19], v[42:43], v[0:1] op_sel_hi:[1,0]
	s_nop 0
	v_pk_mul_f32 v[24:25], v[62:63], v[18:19]
	v_mul_f32_e32 v18, v36, v0
	v_mul_f32_e32 v66, v52, v18
	v_mul_f32_e32 v18, v40, v0
	v_mul_f32_e32 v68, v56, v18
	v_mul_f32_e32 v18, v48, v0
	v_mul_f32_e32 v80, v60, v18
	v_mul_f32_e32 v18, v44, v0
	v_mul_f32_e32 v82, v64, v18
	v_mov_b32_e32 v18, v37
	v_mov_b32_e32 v19, v41
	v_pk_mul_f32 v[22:23], v[18:19], v[0:1] op_sel_hi:[1,0]
	s_nop 0
	v_pk_mul_f32 v[84:85], v[20:21], v[22:23]
	v_mov_b32_e32 v22, v49
	v_mov_b32_e32 v23, v45
	v_pk_mul_f32 v[86:87], v[22:23], v[0:1] op_sel_hi:[1,0]
	s_nop 0
	v_pk_mul_f32 v[86:87], v[26:27], v[86:87]
	s_and_saveexec_b64 s[8:9], s[20:21]
	s_cbranch_execz .LBB0_1284
	global_load_dwordx4 v[90:93], v[78:79], off
	global_load_dwordx4 v[94:97], v[74:75], off
	global_load_dwordx4 v[98:101], v[76:77], off
	global_load_dwordx4 v[102:105], v[72:73], off
	s_waitcnt vmcnt(3)
	v_mul_f32_e32 v110, v66, v92
	s_waitcnt vmcnt(2)
	v_mul_f32_e32 v112, v68, v96
	v_mul_f32_e32 v68, v68, v92
	v_mov_b32_e32 v92, v97
	v_mul_f32_e32 v114, v66, v96
	s_waitcnt vmcnt(1)
	v_mul_f32_e32 v116, v80, v100
	s_waitcnt vmcnt(0)
	v_mul_f32_e32 v118, v82, v104
	v_mul_f32_e32 v82, v82, v100
	v_mul_f32_e32 v120, v80, v104
	v_mov_b32_e32 v96, v93
	v_pk_mul_f32 v[80:81], v[84:85], v[92:93]
	v_mov_b32_e32 v104, v101
	v_mov_b32_e32 v100, v105
	v_pk_mul_f32 v[66:67], v[84:85], v[96:97]
	v_mov_b32_e32 v69, v81
	v_mov_b32_e32 v115, v80
	v_pk_mul_f32 v[80:81], v[86:87], v[104:105]
	v_pk_mul_f32 v[84:85], v[86:87], v[100:101]
	v_mov_b32_e32 v111, v66
	v_mov_b32_e32 v113, v67
	v_mov_b32_e32 v117, v80
	v_mov_b32_e32 v119, v81
	v_mov_b32_e32 v83, v85
	v_mov_b32_e32 v121, v84
	v_pk_mul_f32 v[106:107], v[30:31], v[94:95]
	v_pk_mul_f32 v[94:95], v[32:33], v[94:95]
	v_pk_mul_f32 v[108:109], v[24:25], v[102:103]
	v_pk_mul_f32 v[102:103], v[28:29], v[102:103]
	v_pk_add_f32 v[66:67], v[110:111], v[112:113] neg_lo:[0,1] neg_hi:[0,1]
	v_pk_add_f32 v[68:69], v[68:69], v[114:115]
	v_pk_add_f32 v[80:81], v[116:117], v[118:119] neg_lo:[0,1] neg_hi:[0,1]
	v_pk_add_f32 v[82:83], v[82:83], v[120:121]
	v_pk_fma_f32 v[32:33], v[32:33], v[90:91], v[106:107] neg_lo:[0,0,1] neg_hi:[0,0,1]
	v_pk_fma_f32 v[30:31], v[30:31], v[90:91], v[94:95]
	v_pk_fma_f32 v[28:29], v[28:29], v[98:99], v[108:109] neg_lo:[0,0,1] neg_hi:[0,0,1]
	v_pk_fma_f32 v[24:25], v[24:25], v[98:99], v[102:103]
	v_mov_b32_e32 v84, v67
	v_mov_b32_e32 v85, v69
	v_mov_b32_e32 v86, v81
	v_mov_b32_e32 v87, v83
